# reto item-start waits relaxed (counted instead of vmcnt(0)); GEMM: first two waits of a unit after an epilogue no longer wait for the epilogue stores
# baseline (speedup 1.0000x reference)
.LBB0_294:
	s_add_i32 s22, s10, 2
	s_add_u32 s23, s2, 0x80
	s_addc_u32 s11, s3, 0
	s_add_i32 s41, 0, 0x10000
	s_cmp_eq_u32 s75, s10
	s_cselect_b32 s11, s83, s11
	s_cselect_b32 s10, s82, s23
	v_add_u32_e32 v0, s41, v153
	s_cselect_b32 s45, s95, s21
	s_cselect_b32 s44, s94, s20
	s_add_i32 s23, 0, 0x14000
	ds_read_b128 v[130:133], v0
	ds_read_b128 v[134:137], v0 offset:1024
	ds_read_b128 v[160:163], v0 offset:2048
	ds_read_b128 v[164:167], v0 offset:3072
	v_add_u32_e32 v0, s23, v153
	ds_read_b128 v[168:171], v0
	ds_read_b128 v[172:175], v0 offset:1024
	ds_read_b128 v[202:205], v0 offset:2048
	ds_read_b128 v[206:209], v0 offset:3072
	s_add_i32 m0, s29, 0xc000
	ds_read_b128 v[210:213], v201
	ds_read_b128 v[214:217], v201 offset:1024
	ds_read_b128 v[218:221], v201 offset:2048
	ds_read_b128 v[222:225], v201 offset:3072
	ds_read_b128 v[226:229], v201 offset:4096
	ds_read_b128 v[230:233], v201 offset:5120
	ds_read_b128 v[234:237], v201 offset:6144
	ds_read_b128 v[238:241], v201 offset:7168
	global_load_lds_dwordx4 v156, s[2:3]
	s_add_i32 m0, s29, 0xe000
	s_nop 0
	global_load_lds_dwordx4 v158, s[2:3]
	s_cmp_lg_u32 s22, 2
	s_cbranch_scc1 .Lmy_w0n
	s_cmp_eq_u32 s74, 1
	s_cbranch_scc1 .Lmy_w0n
	v_readlane_b32 vcc_lo, v255, 22
	s_cmp_eq_u32 vcc_lo, 1
	s_cbranch_scc1 .Lmy_w0r
	s_waitcnt vmcnt(16)
	s_branch .Lmy_w0d
.Lmy_w0r:
	s_waitcnt vmcnt(40)
	s_branch .Lmy_w0d
.Lmy_w0n:
	s_waitcnt vmcnt(8)
.Lmy_w0d:
	s_waitcnt lgkmcnt(0)
	s_barrier
	s_setprio 1
	s_waitcnt lgkmcnt(0)
	v_mfma_f32_16x16x32_bf16 v[126:129], v[130:133], v[210:213], v[126:129]
	v_mfma_f32_16x16x32_bf16 v[122:125], v[160:163], v[210:213], v[122:125]
	v_mfma_f32_16x16x32_bf16 v[110:113], v[130:133], v[218:221], v[110:113]
	v_mfma_f32_16x16x32_bf16 v[106:109], v[160:163], v[218:221], v[106:109]
	v_mfma_f32_16x16x32_bf16 v[94:97], v[130:133], v[226:229], v[94:97]
	v_mfma_f32_16x16x32_bf16 v[90:93], v[160:163], v[226:229], v[90:93]
	v_mfma_f32_16x16x32_bf16 v[78:81], v[130:133], v[234:237], v[78:81]
	v_mfma_f32_16x16x32_bf16 v[74:77], v[160:163], v[234:237], v[74:77]
	v_mfma_f32_16x16x32_bf16 v[126:129], v[134:137], v[214:217], v[126:129]
	v_mfma_f32_16x16x32_bf16 v[122:125], v[164:167], v[214:217], v[122:125]
	v_mfma_f32_16x16x32_bf16 v[110:113], v[134:137], v[222:225], v[110:113]
	v_mfma_f32_16x16x32_bf16 v[106:109], v[164:167], v[222:225], v[106:109]
	v_mfma_f32_16x16x32_bf16 v[94:97], v[134:137], v[230:233], v[94:97]
	v_mfma_f32_16x16x32_bf16 v[90:93], v[164:167], v[230:233], v[90:93]
	v_mfma_f32_16x16x32_bf16 v[78:81], v[134:137], v[238:241], v[78:81]
	v_mfma_f32_16x16x32_bf16 v[74:77], v[164:167], v[238:241], v[74:77]
	s_setprio 0
	s_setprio 1
	v_mfma_f32_16x16x32_bf16 v[118:121], v[168:171], v[210:213], v[118:121]
	v_mfma_f32_16x16x32_bf16 v[114:117], v[202:205], v[210:213], v[114:117]
	v_mfma_f32_16x16x32_bf16 v[102:105], v[168:171], v[218:221], v[102:105]
	v_mfma_f32_16x16x32_bf16 v[98:101], v[202:205], v[218:221], v[98:101]
	v_mfma_f32_16x16x32_bf16 v[86:89], v[168:171], v[226:229], v[86:89]
	v_mfma_f32_16x16x32_bf16 v[82:85], v[202:205], v[226:229], v[82:85]
	v_mfma_f32_16x16x32_bf16 v[70:73], v[168:171], v[234:237], v[70:73]
	v_mfma_f32_16x16x32_bf16 v[66:69], v[202:205], v[234:237], v[66:69]
	v_mfma_f32_16x16x32_bf16 v[118:121], v[172:175], v[214:217], v[118:121]
	v_mfma_f32_16x16x32_bf16 v[114:117], v[206:209], v[214:217], v[114:117]
	v_mfma_f32_16x16x32_bf16 v[102:105], v[172:175], v[222:225], v[102:105]
	v_mfma_f32_16x16x32_bf16 v[98:101], v[206:209], v[222:225], v[98:101]
	v_mfma_f32_16x16x32_bf16 v[86:89], v[172:175], v[230:233], v[86:89]
	v_mfma_f32_16x16x32_bf16 v[82:85], v[206:209], v[230:233], v[82:85]
	v_mfma_f32_16x16x32_bf16 v[70:73], v[172:175], v[238:241], v[70:73]
	v_mfma_f32_16x16x32_bf16 v[66:69], v[206:209], v[238:241], v[66:69]
	s_setprio 0
	s_barrier
	s_add_i32 s41, s41, s79
	s_mov_b32 m0, s41
	ds_read_b128 v[210:213], v201 offset:16384
	ds_read_b128 v[214:217], v201 offset:17408
	ds_read_b128 v[218:221], v201 offset:18432
	ds_read_b128 v[222:225], v201 offset:19456
	ds_read_b128 v[226:229], v201 offset:20480
	ds_read_b128 v[230:233], v201 offset:21504
	ds_read_b128 v[234:237], v201 offset:22528
	ds_read_b128 v[238:241], v201 offset:23552
	global_load_lds_dwordx4 v146, s[44:45]
	s_add_i32 m0, s41, 0x2000
	s_add_u32 s98, s44, 0x80
	s_addc_u32 s99, s45, 0
	global_load_lds_dwordx4 v150, s[44:45]
	s_add_u32 s44, s44, s76
	s_addc_u32 s45, s45, 0
	s_add_i32 s23, s23, s79
	s_mov_b32 m0, s23
	s_add_u32 s100, s10, 0x80
	s_addc_u32 s101, s11, 0
	global_load_lds_dwordx4 v146, s[44:45]
	s_add_i32 m0, s23, 0x2000
	s_nop 0
	global_load_lds_dwordx4 v150, s[44:45]
	s_mov_b32 m0, s29
	s_nop 0
	global_load_lds_dwordx4 v144, s[10:11]
	s_mov_b32 m0, s93
	s_nop 0
	global_load_lds_dwordx4 v148, s[10:11]
	s_cmp_lg_u32 s22, 2
	s_cbranch_scc1 .Lmy_w1n
	s_cmp_eq_u32 s74, 1
	s_cbranch_scc1 .Lmy_w1n
	v_readlane_b32 vcc_lo, v255, 22
	s_cmp_eq_u32 vcc_lo, 1
	s_cbranch_scc1 .Lmy_w1r
	s_waitcnt vmcnt(16)
	s_branch .Lmy_w1d

.Lmy_w1d:
	s_waitcnt lgkmcnt(0)
	s_barrier
	s_setprio 1
	s_waitcnt lgkmcnt(0)
	v_mfma_f32_16x16x32_bf16 v[62:65], v[130:133], v[210:213], v[62:65]
	v_mfma_f32_16x16x32_bf16 v[58:61], v[160:163], v[210:213], v[58:61]
	v_mfma_f32_16x16x32_bf16 v[46:49], v[130:133], v[218:221], v[46:49]
	v_mfma_f32_16x16x32_bf16 v[42:45], v[160:163], v[218:221], v[42:45]
	v_mfma_f32_16x16x32_bf16 v[30:33], v[130:133], v[226:229], v[30:33]
	v_mfma_f32_16x16x32_bf16 v[26:29], v[160:163], v[226:229], v[26:29]
	v_mfma_f32_16x16x32_bf16 v[14:17], v[130:133], v[234:237], v[14:17]
	v_mfma_f32_16x16x32_bf16 v[10:13], v[160:163], v[234:237], v[10:13]
	v_mfma_f32_16x16x32_bf16 v[62:65], v[134:137], v[214:217], v[62:65]
	v_mfma_f32_16x16x32_bf16 v[58:61], v[164:167], v[214:217], v[58:61]
	v_mfma_f32_16x16x32_bf16 v[46:49], v[134:137], v[222:225], v[46:49]
	v_mfma_f32_16x16x32_bf16 v[42:45], v[164:167], v[222:225], v[42:45]
	v_mfma_f32_16x16x32_bf16 v[30:33], v[134:137], v[230:233], v[30:33]
	v_mfma_f32_16x16x32_bf16 v[26:29], v[164:167], v[230:233], v[26:29]
	v_mfma_f32_16x16x32_bf16 v[14:17], v[134:137], v[238:241], v[14:17]
	v_mfma_f32_16x16x32_bf16 v[10:13], v[164:167], v[238:241], v[10:13]
	s_setprio 0
	s_setprio 1
	v_mfma_f32_16x16x32_bf16 v[54:57], v[168:171], v[210:213], v[54:57]
	v_mfma_f32_16x16x32_bf16 v[50:53], v[202:205], v[210:213], v[50:53]
	v_mfma_f32_16x16x32_bf16 v[38:41], v[168:171], v[218:221], v[38:41]
	v_mfma_f32_16x16x32_bf16 v[34:37], v[202:205], v[218:221], v[34:37]
	v_mfma_f32_16x16x32_bf16 v[22:25], v[168:171], v[226:229], v[22:25]
	v_mfma_f32_16x16x32_bf16 v[18:21], v[202:205], v[226:229], v[18:21]
	v_mfma_f32_16x16x32_bf16 v[6:9], v[168:171], v[234:237], v[6:9]
	v_mfma_f32_16x16x32_bf16 v[2:5], v[202:205], v[234:237], v[2:5]
	v_mfma_f32_16x16x32_bf16 v[54:57], v[172:175], v[214:217], v[54:57]
	v_mfma_f32_16x16x32_bf16 v[50:53], v[206:209], v[214:217], v[50:53]
	v_mfma_f32_16x16x32_bf16 v[38:41], v[172:175], v[222:225], v[38:41]
	v_mfma_f32_16x16x32_bf16 v[34:37], v[206:209], v[222:225], v[34:37]
	v_mfma_f32_16x16x32_bf16 v[22:25], v[172:175], v[230:233], v[22:25]
	v_mfma_f32_16x16x32_bf16 v[18:21], v[206:209], v[230:233], v[18:21]
	v_mfma_f32_16x16x32_bf16 v[6:9], v[172:175], v[238:241], v[6:9]
	v_mfma_f32_16x16x32_bf16 v[2:5], v[206:209], v[238:241], v[2:5]
	s_setprio 0
	s_barrier
	s_add_i32 s23, 0, 0x18000
	v_add_u32_e32 v0, s23, v153
	s_add_i32 s41, 0, 0x1c000
	ds_read_b128 v[130:133], v0
	ds_read_b128 v[134:137], v0 offset:1024
	ds_read_b128 v[160:163], v0 offset:2048
	ds_read_b128 v[164:167], v0 offset:3072
	v_add_u32_e32 v0, s41, v153
	ds_read_b128 v[168:171], v0
	ds_read_b128 v[172:175], v0 offset:1024
	ds_read_b128 v[202:205], v0 offset:2048
	ds_read_b128 v[206:209], v0 offset:3072
	s_add_u32 s10, s10, s76
	s_addc_u32 s11, s11, 0
	s_mov_b32 m0, s52
	ds_read_b128 v[210:213], v201 offset:32768
	ds_read_b128 v[214:217], v201 offset:33792
	ds_read_b128 v[218:221], v201 offset:34816
	ds_read_b128 v[222:225], v201 offset:35840
	ds_read_b128 v[226:229], v201 offset:36864
	ds_read_b128 v[230:233], v201 offset:37888
	ds_read_b128 v[234:237], v201 offset:38912
	ds_read_b128 v[238:241], v201 offset:39936
	global_load_lds_dwordx4 v144, s[10:11]
	s_mov_b32 m0, s53
	s_nop 0
	global_load_lds_dwordx4 v148, s[10:11]
	s_waitcnt vmcnt(8)
	s_waitcnt lgkmcnt(0)
	s_barrier
	s_setprio 1
	s_waitcnt lgkmcnt(0)
	v_mfma_f32_16x16x32_bf16 v[126:129], v[130:133], v[210:213], v[126:129]
	v_mfma_f32_16x16x32_bf16 v[122:125], v[160:163], v[210:213], v[122:125]
	v_mfma_f32_16x16x32_bf16 v[110:113], v[130:133], v[218:221], v[110:113]
	v_mfma_f32_16x16x32_bf16 v[106:109], v[160:163], v[218:221], v[106:109]
	v_mfma_f32_16x16x32_bf16 v[94:97], v[130:133], v[226:229], v[94:97]
	v_mfma_f32_16x16x32_bf16 v[90:93], v[160:163], v[226:229], v[90:93]
	v_mfma_f32_16x16x32_bf16 v[78:81], v[130:133], v[234:237], v[78:81]
	v_mfma_f32_16x16x32_bf16 v[74:77], v[160:163], v[234:237], v[74:77]
	v_mfma_f32_16x16x32_bf16 v[126:129], v[134:137], v[214:217], v[126:129]
	v_mfma_f32_16x16x32_bf16 v[122:125], v[164:167], v[214:217], v[122:125]
	v_mfma_f32_16x16x32_bf16 v[110:113], v[134:137], v[222:225], v[110:113]
	v_mfma_f32_16x16x32_bf16 v[106:109], v[164:167], v[222:225], v[106:109]
	v_mfma_f32_16x16x32_bf16 v[94:97], v[134:137], v[230:233], v[94:97]
	v_mfma_f32_16x16x32_bf16 v[90:93], v[164:167], v[230:233], v[90:93]
	v_mfma_f32_16x16x32_bf16 v[78:81], v[134:137], v[238:241], v[78:81]
	v_mfma_f32_16x16x32_bf16 v[74:77], v[164:167], v[238:241], v[74:77]
	s_setprio 0
	s_setprio 1
	v_mfma_f32_16x16x32_bf16 v[118:121], v[168:171], v[210:213], v[118:121]
	v_mfma_f32_16x16x32_bf16 v[114:117], v[202:205], v[210:213], v[114:117]
	v_mfma_f32_16x16x32_bf16 v[102:105], v[168:171], v[218:221], v[102:105]
	v_mfma_f32_16x16x32_bf16 v[98:101], v[202:205], v[218:221], v[98:101]
	v_mfma_f32_16x16x32_bf16 v[86:89], v[168:171], v[226:229], v[86:89]
	v_mfma_f32_16x16x32_bf16 v[82:85], v[202:205], v[226:229], v[82:85]
	v_mfma_f32_16x16x32_bf16 v[70:73], v[168:171], v[234:237], v[70:73]
	v_mfma_f32_16x16x32_bf16 v[66:69], v[202:205], v[234:237], v[66:69]
	v_mfma_f32_16x16x32_bf16 v[118:121], v[172:175], v[214:217], v[118:121]
	v_mfma_f32_16x16x32_bf16 v[114:117], v[206:209], v[214:217], v[114:117]
	v_mfma_f32_16x16x32_bf16 v[102:105], v[172:175], v[222:225], v[102:105]
	v_mfma_f32_16x16x32_bf16 v[98:101], v[206:209], v[222:225], v[98:101]
	v_mfma_f32_16x16x32_bf16 v[86:89], v[172:175], v[230:233], v[86:89]
	v_mfma_f32_16x16x32_bf16 v[82:85], v[206:209], v[230:233], v[82:85]
	v_mfma_f32_16x16x32_bf16 v[70:73], v[172:175], v[238:241], v[70:73]
	v_mfma_f32_16x16x32_bf16 v[66:69], v[206:209], v[238:241], v[66:69]
	s_setprio 0
	s_barrier
	s_add_i32 s10, s23, s79
	s_mov_b32 m0, s10
	ds_read_b128 v[210:213], v201 offset:49152
	ds_read_b128 v[214:217], v201 offset:50176
	ds_read_b128 v[218:221], v201 offset:51200
	ds_read_b128 v[222:225], v201 offset:52224
	ds_read_b128 v[226:229], v201 offset:53248
	ds_read_b128 v[230:233], v201 offset:54272
	ds_read_b128 v[234:237], v201 offset:55296
	ds_read_b128 v[238:241], v201 offset:56320
	global_load_lds_dwordx4 v146, s[98:99]
	s_add_i32 m0, s10, 0x2000
	s_add_i32 s10, s41, s79
	global_load_lds_dwordx4 v150, s[98:99]
	s_add_u32 s98, s98, s76
	s_addc_u32 s99, s99, 0
	s_mov_b32 m0, s10
	s_nop 0
	global_load_lds_dwordx4 v146, s[98:99]
	s_add_i32 m0, s10, 0x2000
	s_nop 0
	global_load_lds_dwordx4 v150, s[98:99]
	s_mov_b32 m0, s26
	s_nop 0
	global_load_lds_dwordx4 v144, s[100:101]
	s_mov_b32 m0, s27
	s_nop 0
	global_load_lds_dwordx4 v148, s[100:101]
	s_waitcnt vmcnt(8)
	s_waitcnt lgkmcnt(0)
	s_barrier
	s_setprio 1
	s_waitcnt lgkmcnt(0)
	v_mfma_f32_16x16x32_bf16 v[62:65], v[130:133], v[210:213], v[62:65]
	v_mfma_f32_16x16x32_bf16 v[58:61], v[160:163], v[210:213], v[58:61]
	v_mfma_f32_16x16x32_bf16 v[46:49], v[130:133], v[218:221], v[46:49]
	v_mfma_f32_16x16x32_bf16 v[42:45], v[160:163], v[218:221], v[42:45]
	v_mfma_f32_16x16x32_bf16 v[30:33], v[130:133], v[226:229], v[30:33]
	v_mfma_f32_16x16x32_bf16 v[26:29], v[160:163], v[226:229], v[26:29]
	v_mfma_f32_16x16x32_bf16 v[14:17], v[130:133], v[234:237], v[14:17]
	v_mfma_f32_16x16x32_bf16 v[10:13], v[160:163], v[234:237], v[10:13]
	v_mfma_f32_16x16x32_bf16 v[62:65], v[134:137], v[214:217], v[62:65]
	v_mfma_f32_16x16x32_bf16 v[58:61], v[164:167], v[214:217], v[58:61]
	v_mfma_f32_16x16x32_bf16 v[46:49], v[134:137], v[222:225], v[46:49]
	v_mfma_f32_16x16x32_bf16 v[42:45], v[164:167], v[222:225], v[42:45]
	v_mfma_f32_16x16x32_bf16 v[30:33], v[134:137], v[230:233], v[30:33]
	v_mfma_f32_16x16x32_bf16 v[26:29], v[164:167], v[230:233], v[26:29]
	v_mfma_f32_16x16x32_bf16 v[14:17], v[134:137], v[238:241], v[14:17]
	v_mfma_f32_16x16x32_bf16 v[10:13], v[164:167], v[238:241], v[10:13]
	s_setprio 0
	s_setprio 1
	v_mfma_f32_16x16x32_bf16 v[54:57], v[168:171], v[210:213], v[54:57]
	v_mfma_f32_16x16x32_bf16 v[50:53], v[202:205], v[210:213], v[50:53]
	v_mfma_f32_16x16x32_bf16 v[38:41], v[168:171], v[218:221], v[38:41]
	v_mfma_f32_16x16x32_bf16 v[34:37], v[202:205], v[218:221], v[34:37]
	v_mfma_f32_16x16x32_bf16 v[22:25], v[168:171], v[226:229], v[22:25]
	v_mfma_f32_16x16x32_bf16 v[18:21], v[202:205], v[226:229], v[18:21]
	v_mfma_f32_16x16x32_bf16 v[6:9], v[168:171], v[234:237], v[6:9]
	v_mfma_f32_16x16x32_bf16 v[2:5], v[202:205], v[234:237], v[2:5]
	v_mfma_f32_16x16x32_bf16 v[54:57], v[172:175], v[214:217], v[54:57]
	v_mfma_f32_16x16x32_bf16 v[50:53], v[206:209], v[214:217], v[50:53]
	v_mfma_f32_16x16x32_bf16 v[38:41], v[172:175], v[222:225], v[38:41]
	v_mfma_f32_16x16x32_bf16 v[34:37], v[206:209], v[222:225], v[34:37]
	v_mfma_f32_16x16x32_bf16 v[22:25], v[172:175], v[230:233], v[22:25]
	v_mfma_f32_16x16x32_bf16 v[18:21], v[206:209], v[230:233], v[18:21]
	v_mfma_f32_16x16x32_bf16 v[6:9], v[172:175], v[238:241], v[6:9]
	v_mfma_f32_16x16x32_bf16 v[2:5], v[206:209], v[238:241], v[2:5]
	s_setprio 0
	s_barrier
	s_add_u32 s2, s2, 0x100
	s_addc_u32 s3, s3, 0
	s_add_u32 s20, s20, 0x100
	s_addc_u32 s21, s21, 0
	s_cmp_ge_u32 s22, s63
	s_mov_b32 s10, s22
	s_cbranch_scc0 .LBB0_294
	v_readlane_b32 s2, v255, 24
	v_readlane_b32 s3, v255, 25
	s_and_b64 vcc, exec, s[2:3]
	s_cbranch_vccz .LBB0_297
	s_barrier
